# P1 GEMM: column blocks of XM computed last (blocks 16-23 and 24-31 swapped in the tile order) so mqk finds XM in cache
# speedup vs baseline: 1.0008x; 1.0008x over previous
; template <class Epi>
; __device__ __forceinline__ void gemm_phase(PG8_LAS unsigned char* lds, const Gemm g, const StaticOrder& S, const Epi& E) {
;     ...
;         const bool has_next = S.next(ui + 1, nxt);
;         const char* nA = has_next ? (const char*)g.A + (size_t)nxt.pm * tstep : cA; const char* nB = has_next ? (const char*)g.Bt + (size_t)nxt.pn * tstep : cB;
;     ...
; #pragma unroll
;         for (int a = 0; a < 2; ++a)
; #pragma unroll
;             for (int b = 0; b < 2; ++b)
; #pragma unroll
;                 for (int m = 0; m < 4; ++m)
; #pragma unroll
;                     for (int n = 0; n < 2; ++n) acc[a][b][m][n] = (f32x4){0.f, 0.f, 0.f, 0.f};
;         cur = nxt; cA = nA; cB = nB; ++ui;
.LBB0_55:
	s_bfe_u32 s17, s16, 0x10004
	s_lshl_b32 s17, s17, 3
	s_xor_b32 s16, s16, s17
	s_ashr_i32 s19, s18, 31
	v_cmp_lt_i64_e32 vcc, s[20:21], v[144:145]
	s_lshl_b64 s[20:21], s[18:19], 20
	s_add_u32 s20, s64, s20
	s_addc_u32 s21, s65, s21
	s_and_b64 s[22:23], vcc, exec
	s_cselect_b32 s5, s21, s27
	s_cselect_b32 s19, s20, s26
	s_ashr_i32 s17, s16, 31
	s_lshl_b64 s[22:23], s[16:17], 20
	s_add_u32 s22, s34, s22
	s_addc_u32 s23, s35, s23
	s_and_b64 s[30:31], vcc, exec
	s_cselect_b32 s17, s23, s29
	s_cselect_b32 s25, s22, s28
	s_add_u32 s26, s26, 0x80080
	s_addc_u32 s27, s27, 0
	s_add_u32 s48, s28, 0x100
	v_mov_b32_e32 v2, 0
	s_addc_u32 s49, s29, 0
	s_mov_b32 s50, -2
	v_mov_b32_e32 v3, v2
	v_mov_b32_e32 v4, v2
	v_mov_b32_e32 v5, v2
	v_mov_b32_e32 v6, v2
	v_mov_b32_e32 v7, v2
	v_mov_b32_e32 v8, v2
	v_mov_b32_e32 v9, v2
	v_mov_b32_e32 v18, v2
	v_mov_b32_e32 v19, v2
	v_mov_b32_e32 v20, v2
	v_mov_b32_e32 v21, v2
	v_mov_b32_e32 v22, v2
	v_mov_b32_e32 v23, v2
	v_mov_b32_e32 v24, v2
	v_mov_b32_e32 v25, v2
	v_mov_b32_e32 v34, v2
	v_mov_b32_e32 v35, v2
	v_mov_b32_e32 v36, v2
	v_mov_b32_e32 v37, v2
	v_mov_b32_e32 v38, v2
	v_mov_b32_e32 v39, v2
	v_mov_b32_e32 v40, v2
	v_mov_b32_e32 v41, v2
	v_mov_b32_e32 v50, v2
	v_mov_b32_e32 v51, v2
	v_mov_b32_e32 v52, v2
	v_mov_b32_e32 v53, v2
	v_mov_b32_e32 v54, v2
	v_mov_b32_e32 v55, v2
	v_mov_b32_e32 v56, v2
	v_mov_b32_e32 v57, v2
	v_mov_b32_e32 v10, v2
	v_mov_b32_e32 v11, v2
	v_mov_b32_e32 v12, v2
	v_mov_b32_e32 v13, v2
	v_mov_b32_e32 v14, v2
	v_mov_b32_e32 v15, v2
	v_mov_b32_e32 v16, v2
	v_mov_b32_e32 v17, v2
	v_mov_b32_e32 v26, v2
	v_mov_b32_e32 v27, v2
	v_mov_b32_e32 v28, v2
	v_mov_b32_e32 v29, v2
	v_mov_b32_e32 v30, v2
	v_mov_b32_e32 v31, v2
	v_mov_b32_e32 v32, v2
	v_mov_b32_e32 v33, v2
	v_mov_b32_e32 v42, v2
	v_mov_b32_e32 v43, v2
	v_mov_b32_e32 v44, v2
	v_mov_b32_e32 v45, v2
	v_mov_b32_e32 v46, v2
	v_mov_b32_e32 v47, v2
	v_mov_b32_e32 v48, v2
	v_mov_b32_e32 v49, v2
	v_mov_b32_e32 v58, v2
	v_mov_b32_e32 v59, v2
	v_mov_b32_e32 v60, v2
	v_mov_b32_e32 v61, v2
	v_mov_b32_e32 v62, v2
	v_mov_b32_e32 v63, v2
	v_mov_b32_e32 v64, v2
	v_mov_b32_e32 v65, v2
	v_mov_b32_e32 v66, v2
	v_mov_b32_e32 v67, v2
	v_mov_b32_e32 v68, v2
	v_mov_b32_e32 v69, v2
	v_mov_b32_e32 v70, v2
	v_mov_b32_e32 v71, v2
	v_mov_b32_e32 v72, v2
	v_mov_b32_e32 v73, v2
	v_mov_b32_e32 v82, v2
	v_mov_b32_e32 v83, v2
	v_mov_b32_e32 v84, v2
	v_mov_b32_e32 v85, v2
	v_mov_b32_e32 v86, v2
	v_mov_b32_e32 v87, v2
	v_mov_b32_e32 v88, v2
	v_mov_b32_e32 v89, v2
	v_mov_b32_e32 v98, v2
	v_mov_b32_e32 v99, v2
	v_mov_b32_e32 v100, v2
	v_mov_b32_e32 v101, v2
	v_mov_b32_e32 v102, v2
	v_mov_b32_e32 v103, v2
	v_mov_b32_e32 v104, v2
	v_mov_b32_e32 v105, v2
	v_mov_b32_e32 v114, v2
	v_mov_b32_e32 v115, v2
	v_mov_b32_e32 v116, v2
	v_mov_b32_e32 v117, v2
	v_mov_b32_e32 v118, v2
	v_mov_b32_e32 v119, v2
	v_mov_b32_e32 v120, v2
	v_mov_b32_e32 v121, v2
	v_mov_b32_e32 v74, v2
	v_mov_b32_e32 v75, v2
	v_mov_b32_e32 v76, v2
	v_mov_b32_e32 v77, v2
	v_mov_b32_e32 v78, v2
	v_mov_b32_e32 v79, v2
	v_mov_b32_e32 v80, v2
	v_mov_b32_e32 v81, v2
	v_mov_b32_e32 v90, v2
	v_mov_b32_e32 v91, v2
	v_mov_b32_e32 v92, v2
	v_mov_b32_e32 v93, v2
	v_mov_b32_e32 v94, v2
	v_mov_b32_e32 v95, v2
	v_mov_b32_e32 v96, v2
	v_mov_b32_e32 v97, v2
	v_mov_b32_e32 v106, v2
	v_mov_b32_e32 v107, v2
	v_mov_b32_e32 v108, v2
	v_mov_b32_e32 v109, v2
	v_mov_b32_e32 v110, v2
	v_mov_b32_e32 v111, v2
	v_mov_b32_e32 v112, v2
	v_mov_b32_e32 v113, v2
	v_mov_b32_e32 v122, v2
	v_mov_b32_e32 v123, v2
	v_mov_b32_e32 v124, v2
	v_mov_b32_e32 v125, v2
	v_mov_b32_e32 v126, v2
	v_mov_b32_e32 v127, v2
	v_mov_b32_e32 v128, v2
	v_mov_b32_e32 v129, v2
